# combined version plus layer-0 odd workgroups running the GLA output stage before their NSA units
# baseline (speedup 1.0000x reference)
; DI void nsa_unit(const Ctx& c0, int b, int g, int i, LAS unsigned char* lds) {
;     const Ctx c = launder(c0);
;     const int tid = c.tid, lane = c.lane, wid = c.wid, r = lane & 31, hi = lane >> 5;
;     const int hl = wid >> 1, qh = wid & 1, head = g * 4 + hl, ql = 32 * qh + r, t = i * 64 + ql;
;     const size_t row = (size_t)b * SEQ + t;
;     LAS float* wsf = (LAS float*)(lds + A_WSF) + wid * 64;
;     LAS float* IMP = (LAS float*)(lds + A_IMP);
;     LAS unsigned long long* SEL = (LAS unsigned long long*)(lds + A_SEL);
;     const bf16* misc = (const bf16*)(c.ws + O_MISC);
;     bf16x8 qn[4];
;     { const bf16* qp = (const bf16*)(c.ws + O_QN) + row * 512 + head * 64 + 8 * hi;
; #pragma unroll
;       for (int s = 0; s < 4; ++s) qn[s] = *(const bf16x8*)(qp + 16 * s); }
;     const float g_c = sigmoidf_(bf2f(misc[row * 64 + head * 3 + 0])), g_s = sigmoidf_(bf2f(misc[row * 64 + head * 3 + 1])), g_w = sigmoidf_(bf2f(misc[row * 64 + head * 3 + 2]));
;     ...
;     const float g_c2 = 0.f;
;     ...
;     const float g_c2 = g_c;
;     ...
;     const float g_s2 = 0.f;
;     ...
;     const float g_s2 = g_s;
;     ...
;     const float g_w2 = 0.f;
;     ...
;     const float g_w2 = g_w;
;     ...
;     f32x16 dum0 = {}, dum1 = {};
;     LAS float* OACC = (LAS float*)(lds + A_IMP) + wid * 2048 + lane;
;     LAS unsigned* OC = (LAS unsigned*)(lds + A_OC) + wid * 1024 + lane;
;     f32x16 ca0, ca1;
;     ...
;     {
;         const bf16* Kg = (const bf16*)(c.ws + O_KCMP) + ((size_t)(0 + g) * 2048 + b * 256) * 64;
;         const bf16* Vg = (const bf16*)(c.ws + O_KCMP) + ((size_t)(2 + g) * 2048 + b * 256) * 64;
;         const int nt = (4 * i + 3 + 63) >> 6;
;         const int jmax = (t - 31) >> 4;
;         ASt st; st.m = NEGB; st.l = 0.f; st.o0 = f32x16{}; st.o1 = f32x16{};
;         f32x16 imp0 = {}, imp1 = {};
;         TileRegs tr = tile_fetch(Kg, Vg, 0, tid);
;         for (int k = 0; k < nt; ++k) {
;             tile_stage(tr, lds, k & 1, tid);
;             __syncthreads();
;             if (k + 1 < nt) tr = tile_fetch(Kg, Vg, 64 * (k + 1), tid);
; template <int PH> DI void run_phase(const Ctx& cb, LAS unsigned char* lds, int layer) {
;     ...
;         for (int sl = cb.vcu; sl < 256; sl += cb.G) { const int bg = sl >> 4, s = sl & 15;
; #pragma unroll 1
;             for (int it = 0; it < 4; ++it) { const int i = (it == 0) ? s : (it == 1) ? 31 - s : (it == 2) ? 32 + s : 63 - s; nsa_unit(cb, bg >> 1, bg & 1, i, lds); } }
.LBB0_536:
	s_andn2_b64 vcc, exec, s[0:1]
	v_lshlrev_b32_e32 v189, 2, v150
	v_cmp_gt_u32_e64 s[4:5], 32, v150
	v_lshrrev_b32_e32 v192, 1, v150
	v_lshlrev_b32_e32 v191, 4, v151
	v_and_b32_e32 v190, 7, v151
	s_cbranch_vccnz .LBB0_602
	v_readlane_b32 s0, v250, 2
	s_and_b32 s0, s0, 1
	s_nop 0
	v_writelane_b32 v250, s0, 60
	s_cmp_eq_u32 s0, 0
	s_cbranch_scc1 .Lswap_A_l0
	s_lshr_b32 s0, s82, 7
	s_nop 0
	v_writelane_b32 v250, s0, 32
	s_branch .LBB0_601
.Lswap_A_l0:
	v_readlane_b32 s3, v250, 4
	s_lshl_b32 s0, s3, 5
	s_and_b32 s33, s0, 32
	s_lshr_b32 s2, s82, 7
	v_or_b32_e32 v125, s33, v152
	v_lshlrev_b32_e32 v148, 2, v153
	v_writelane_b32 v250, s2, 32
	v_cmp_gt_u32_e64 s[8:9], v148, v125
	v_or_b32_e32 v149, 32, v148
	v_or_b32_e32 v155, 33, v148
	v_writelane_b32 v250, s8, 27
	v_lshlrev_b32_e32 v2, 1, v153
	v_or_b32_e32 v156, 2, v148
	v_writelane_b32 v250, s9, 28
	v_cmp_gt_u32_e64 s[8:9], v149, v125
	v_bitop3_b32 v4, v2, v151, 31 bitop3:0x78
	v_lshlrev_b32_e32 v139, 4, v4
	v_writelane_b32 v250, s8, 33
	v_bitop3_b32 v4, v2, v152, 4 bitop3:0x36
	v_or_b32_e32 v157, 34, v148
	v_writelane_b32 v250, s9, 34
	v_cmp_lt_u32_e64 s[8:9], v148, v125
	s_lshl_b32 s1, s3, 12
	v_lshlrev_b32_e32 v143, 4, v4
	v_writelane_b32 v250, s8, 35
	v_bitop3_b32 v4, v2, v152, 8 bitop3:0x36
	v_bitop3_b32 v2, v2, v152, 12 bitop3:0x36
	v_writelane_b32 v250, s9, 36
	v_cmp_gt_u32_e64 s[8:9], v155, v125
	s_lshl_b32 s2, s2, 14
	s_lshl_b32 s0, s3, 8
	v_writelane_b32 v250, s8, 37
	v_lshlrev_b32_e32 v147, 4, v2
	v_or_b32_e32 v158, 3, v148
	v_writelane_b32 v250, s9, 38
	v_cmp_gt_u32_e64 s[8:9], v156, v125
	v_lshlrev_b32_e32 v193, 2, v152
	v_and_or_b32 v2, v188, 3, v148
	v_writelane_b32 v250, s8, 39
	s_add_i32 s1, s1, 0
	s_add_i32 s2, s2, 0
	v_writelane_b32 v250, s9, 40
	v_cmp_gt_u32_e64 s[8:9], v157, v125
	s_add_i32 s16, s0, 0
	v_lshlrev_b32_e32 v137, 10, v153
	v_writelane_b32 v250, s8, 41
	v_lshlrev_b32_e32 v146, 4, v4
	v_lshlrev_b32_e32 v196, 6, v2
	s_add_i32 s1, s1, 0x19200
	v_and_b32_e32 v2, 16, v192
	v_add_u32_e32 v4, s2, v193
	s_add_i32 s2, 0, 0x19000
	v_writelane_b32 v250, s9, 42
	v_cmp_gt_u32_e64 s[8:9], v158, v125
	v_add_u32_e32 v203, s1, v189
	v_add_u32_e32 v205, s16, v2
	v_or_b32_e32 v2, s33, v148
	v_lshl_add_u32 v206, v125, 3, s2
	v_lshl_add_u32 v207, v150, 3, s2
	v_add_u32_e32 v211, 0, v137
	v_writelane_b32 v250, s8, 43
	s_movk_i32 s2, 0xfd00
	v_lshl_add_u32 v7, v190, 4, s1
	v_lshl_add_u32 v12, v153, 9, s1
	s_lshl_b32 s1, s3, 6
	v_and_b32_e32 v197, 32, v187
	v_lshlrev_b32_e32 v5, 8, v2
	v_and_b32_e32 v209, 0xc0, v191
	v_writelane_b32 v250, s9, 44
	v_mad_i32_i24 v2, v153, s2, v211
	v_or_b32_e32 v9, 8, v185
	v_or_b32_e32 v10, 16, v185
	v_or_b32_e32 v11, 24, v185
	s_add_i32 s1, s1, 0x19000
	v_add_u32_e32 v1, 0, v189
	v_mov_b32_e32 v3, 0
	s_lshl_b32 s0, s3, 13
	v_or_b32_e32 v159, 35, v148
	v_or_b32_e32 v160, 8, v148
	v_or_b32_e32 v161, 40, v148
	v_or_b32_e32 v162, 9, v148
	v_or_b32_e32 v163, 41, v148
	v_or_b32_e32 v164, 10, v148
	v_or_b32_e32 v165, 42, v148
	v_or_b32_e32 v166, 11, v148
	v_or_b32_e32 v167, 43, v148
	v_or_b32_e32 v168, 16, v148
	v_or_b32_e32 v169, 48, v148
	v_or_b32_e32 v170, 17, v148
	v_or_b32_e32 v171, 49, v148
	v_or_b32_e32 v172, 18, v148
	v_or_b32_e32 v173, 50, v148
	v_or_b32_e32 v174, 19, v148
	v_or_b32_e32 v175, 51, v148
	v_or_b32_e32 v176, 24, v148
	v_or_b32_e32 v177, 56, v148
	v_or_b32_e32 v178, 25, v148
	v_or_b32_e32 v179, 57, v148
	v_or_b32_e32 v180, 26, v148
	v_or_b32_e32 v181, 58, v148
	v_or_b32_e32 v182, 27, v148
	v_or_b32_e32 v183, 59, v148
	v_and_b32_e32 v198, 24, v186
	v_add3_u32 v6, v2, v209, v197
	v_lshlrev_b32_e32 v2, 3, v190
	v_lshlrev_b32_e32 v8, 7, v185
	v_lshlrev_b32_e32 v128, 10, v9
	v_lshlrev_b32_e32 v9, 7, v9
	v_lshlrev_b32_e32 v130, 10, v10
	v_lshlrev_b32_e32 v10, 7, v10
	v_lshlrev_b32_e32 v132, 10, v11
	v_lshlrev_b32_e32 v11, 7, v11
	v_lshlrev_b32_e32 v13, 1, v152
	v_writelane_b32 v250, s1, 45
	s_mov_b32 s85, 0
	v_lshlrev_b32_e32 v124, 3, v153
	v_or_b32_e32 v154, 1, v148
	v_add_u32_e32 v194, s16, v193
	v_lshlrev_b32_e32 v195, 4, v153
	v_add_u32_e32 v199, -1, v193
	v_or_b32_e32 v200, 3, v193
	v_add_u32_e32 v201, 0x7f, v193
	v_or_b32_e32 v202, 0x83, v193
	v_add_u32_e32 v204, s16, v189
	v_cmp_eq_u32_e64 s[6:7], 0, v150
	v_lshlrev_b32_e32 v208, 8, v153
	v_add_u32_e32 v210, 1, v125
	v_cmp_ne_u32_e64 s[10:11], 63, v125
	v_cmp_gt_u32_e64 s[26:27], v159, v125
	v_cmp_gt_u32_e64 s[28:29], v160, v125
	v_cmp_gt_u32_e64 s[30:31], v161, v125
	v_cmp_gt_u32_e64 s[34:35], v162, v125
	v_cmp_gt_u32_e64 s[36:37], v163, v125
	v_cmp_gt_u32_e64 s[38:39], v164, v125
	v_cmp_gt_u32_e64 s[40:41], v165, v125
	v_cmp_gt_u32_e64 s[42:43], v166, v125
	v_cmp_gt_u32_e64 s[44:45], v167, v125
	v_cmp_gt_u32_e64 s[46:47], v168, v125
	v_cmp_gt_u32_e64 s[48:49], v169, v125
	v_cmp_gt_u32_e64 s[50:51], v170, v125
	v_cmp_gt_u32_e64 s[52:53], v171, v125
	v_cmp_gt_u32_e64 s[54:55], v172, v125
	v_cmp_gt_u32_e64 s[56:57], v173, v125
	v_cmp_gt_u32_e64 s[58:59], v174, v125
	v_cmp_gt_u32_e64 s[60:61], v175, v125
	v_cmp_gt_u32_e64 s[62:63], v176, v125
	v_cmp_gt_u32_e64 s[64:65], v177, v125
	v_cmp_gt_u32_e64 s[66:67], v178, v125
	v_cmp_gt_u32_e64 s[68:69], v179, v125
	v_cmp_gt_u32_e64 s[70:71], v180, v125
	v_cmp_gt_u32_e64 s[72:73], v181, v125
	v_cmp_gt_u32_e64 s[74:75], v182, v125
	v_cmp_gt_u32_e64 s[76:77], v183, v125
	v_lshlrev_b32_e32 v126, 10, v185
	v_mov_b32_e32 v127, v3
	v_mov_b32_e32 v129, v3
	v_mov_b32_e32 v131, v3
	v_mov_b32_e32 v133, v3
	v_lshl_or_b32 v212, s3, 11, v189
	s_mov_b32 s17, 0x5040100
	v_add_u32_e32 v213, v4, v5
	v_add_u32_e32 v214, s0, v1
	v_add_u32_e32 v215, v6, v198
	v_lshlrev_b32_e32 v134, 1, v2
	v_add_u32_e32 v216, v7, v8
	v_add_u32_e32 v217, v7, v9
	v_add_u32_e32 v218, v7, v10
	v_add_u32_e32 v219, v7, v11
	v_add_u32_e32 v220, v12, v13
	v_mbcnt_hi_u32_b32 v221, -1, v184
	v_mov_b32_e32 v222, 0xf149f2ca
	v_mov_b32_e32 v223, 0x7149f2ca
	v_mov_b32_e32 v224, 0x3f80
	v_readlane_b32 s0, v250, 2
	s_branch .LBB0_539

; template <int PH> DI void run_phase(const Ctx& cb, LAS unsigned char* lds, int layer) {
;     ...
;         __syncthreads();
.Lswap_toA_l0:
	s_mov_b32 s1, 2
	s_nop 0
	v_writelane_b32 v250, s1, 60
	s_waitcnt vmcnt(0) lgkmcnt(0)
	s_barrier
	v_readlane_b32 s82, v250, 24
	v_cmp_gt_u32_e64 s[4:5], 32, v150
	s_branch .Lswap_A_l0

; #define LAS __attribute__((address_space(3)))
; DI Ctx launder(const Ctx& c0) { Ctx c = c0; asm volatile("" : "+s"(c.ws), "+s"(c.out), "+v"(c.tid)); return c; }
; DI void gla_stage3(const Ctx& c0, int layer, int unit, int cb, LAS unsigned char* lds) {
;     const Ctx c = launder(c0);
;     const int lane = c.lane, r = lane & 31, hi = lane >> 5;
;     const int bh = unit >> 6, n = unit & 63, b = bh >> 2, h = bh & 3;
;     const size_t row0 = (size_t)b * SEQ + n * 64 + 32 * cb;
;     LAS unsigned char* R = lds + c.wid * G3_BYTES;
;     const LAS unsigned char* Re = R + (4 * hi) * G3_PITCH + r * 2;
;     const bf16* qgp = (const bf16*)(c.ws + O_QG) + (row0 + r) * 256 + h * 64 + 8 * hi;
;     const float* sp = (const float*)(c.ws + O_UPD) + (size_t)unit * 8192;
;     const float* gn = c.a->in[I_GNORM] + (size_t)layer * 128;
; template <int PH> DI void run_phase(const Ctx& cb, LAS unsigned char* lds, int layer) {
;     ...
;         __syncthreads();
;         for (int pu = blockIdx.x * 4 + (cb.wid >> 1); pu < 2048; pu += cb.G * 4) gla_stage3(cb, layer, pu, cb.wid & 1, lds);
.LBB0_602:
	s_lshl_b32 s0, s78, 2
	v_readlane_b32 s1, v250, 32
	s_add_i32 s2, s1, s0
	s_cmpk_lt_i32 s2, 0x800
	s_cselect_b64 s[0:1], -1, 0
	v_writelane_b32 v250, s0, 47
	s_cmpk_gt_i32 s2, 0x7ff
	v_lshrrev_b32_e32 v193, 4, v150
	v_writelane_b32 v250, s1, 48
	s_mov_b32 s0, s2
	v_writelane_b32 v250, s0, 49
	v_and_b32_e32 v194, 15, v151
	s_waitcnt lgkmcnt(0)
	v_writelane_b32 v250, s1, 50
	s_barrier
	v_readlane_b32 s0, v250, 4
	s_mulk_i32 s0, 0x2200
	s_nop 0
	v_writelane_b32 v250, s0, 51
	s_nop 0
	v_readlane_b32 s1, v250, 60
	s_cmp_eq_u32 s1, 2
	s_cbranch_scc1 .LBB0_605
	s_cmpk_gt_i32 s2, 0x7ff
	s_cbranch_scc1 .LBB0_605
	v_readlane_b32 s0, v250, 4
	s_lshl_b32 s0, s0, 5
	s_and_b32 s6, s0, 32
	s_load_dwordx2 s[0:1], s[90:91], 0x58
	v_mov_b32_e32 v67, 0
	v_readlane_b32 s2, v250, 51
	v_lshlrev_b32_e32 v6, 2, v152
	v_mov_b32_e32 v7, v67
	v_mul_u32_u24_e32 v1, 0x440, v153
	v_lshlrev_b32_e32 v3, 1, v152
	s_add_i32 s2, s2, 0
	s_waitcnt lgkmcnt(0)
	v_lshl_add_u64 v[82:83], s[0:1], 0, v[6:7]
	v_readlane_b32 s0, v250, 49
	v_add3_u32 v1, s2, v1, v3
	v_lshl_add_u32 v3, v194, 4, s2
	v_readlane_b32 s1, v250, 50
	s_mov_b32 s2, s0
	s_ashr_i32 s3, s0, 31
	v_lshlrev_b32_e32 v5, 12, v153
	s_lshl_b64 s[0:1], s[2:3], 15
	v_or3_b32 v6, s0, v5, v6
	v_mov_b32_e32 v7, s1
	s_mov_b64 s[0:1], 0x1ba06f80
	v_lshl_add_u64 v[84:85], v[6:7], 0, s[0:1]
	v_readlane_b32 s0, v250, 32
	v_lshlrev_b32_e32 v2, 3, v153
	s_lshl_b32 s12, s70, 2
	s_lshl_b32 s0, s0, 6
	v_readlane_b32 s1, v250, 29
	v_mbcnt_hi_u32_b32 v93, -1, v184
	s_mov_b32 s11, 0
	v_lshlrev_b32_e32 v4, 3, v194
	v_lshlrev_b32_e32 v66, 10, v193
	v_mul_u32_u24_e32 v8, 0x110, v193
	s_ashr_i32 s13, s12, 31
	s_add_i32 s8, s1, s0
	v_lshlrev_b32_e32 v86, 1, v2
	v_and_b32_e32 v2, 64, v93
	s_mov_b32 s0, s2
	s_mov_b32 s7, s11
	v_or_b32_e32 v68, 0x1000, v66
	v_mov_b32_e32 v69, v67
	v_or_b32_e32 v70, 0x2000, v66
	v_mov_b32_e32 v71, v67
	v_or_b32_e32 v72, 0x3000, v66
	v_mov_b32_e32 v73, v67
	v_or_b32_e32 v74, 0x4000, v66
	v_mov_b32_e32 v75, v67
	v_or_b32_e32 v76, 0x5000, v66
	v_mov_b32_e32 v77, v67
	v_or_b32_e32 v78, 0x6000, v66
	v_mov_b32_e32 v79, v67
	v_or_b32_e32 v80, 0x7000, v66
	v_mov_b32_e32 v81, v67
	s_lshl_b64 s[14:15], s[12:13], 15
	s_lshl_b32 s9, s70, 8
	v_mov_b32_e32 v87, v67
	s_mov_b64 s[16:17], 0x4400000
	s_mov_b32 s13, 0x4400000
	s_movk_i32 s24, 0x9080
	s_movk_i32 s25, 0xb080
	s_movk_i32 s26, 0xd080
	s_movk_i32 s27, 0xf080
	s_movk_i32 s28, 0x9100
	s_movk_i32 s29, 0xb100
	s_movk_i32 s30, 0xd100
	s_movk_i32 s31, 0xf100
	v_lshlrev_b32_e32 v88, 1, v4
	v_mov_b32_e32 v89, v67
	s_mov_b64 s[18:19], 0x2400000
	v_add_u32_e32 v92, v3, v8
	v_xor_b32_e32 v94, 1, v93
	v_add_u32_e32 v95, 64, v2
	v_xor_b32_e32 v96, 2, v93
	v_xor_b32_e32 v97, 4, v93
	v_xor_b32_e32 v98, 8, v93
	v_xor_b32_e32 v99, 16, v93
	v_mov_b32_e32 v100, 0x358637bd
	s_mov_b32 s34, 0xf800000
	v_mov_b32_e32 v101, 0x260
	s_mov_b64 s[20:21], 0x11500000
	s_mov_b64 s[22:23], 0xf500000
	v_writelane_b32 v250, s0, 49
	s_mov_b32 s35, s2
	s_nop 0
	v_writelane_b32 v250, s1, 50

; __device__ __forceinline__ unsigned xb_ld(unsigned* p)              { return __hip_atomic_load(p, __ATOMIC_RELAXED, __HIP_MEMORY_SCOPE_AGENT); }
; __device__ __forceinline__ void xcd_barrier_complete(unsigned* bar, unsigned x, unsigned& nloc, unsigned& nx) {
;     const unsigned G = gridDim.x * gridDim.y * gridDim.z;
;     unsigned sum, cnt, mine, sp = 0u;
;     for (;;) {
;         sum = 0u; cnt = 0u; mine = 0u;
; #pragma unroll
;         for (unsigned j = 0; j < 16; ++j) { const unsigned c = xb_ld(&bar[XB_XCNT(j)]); sum += c; cnt += (c > 0u) ? 1u : 0u; mine = (j == x) ? c : mine; }
; __device__ __forceinline__ void xcd_barrier(const XcdBarrier& b) {
;     asm volatile("s_waitcnt vmcnt(0)" ::: "memory");
;     __syncthreads();
;     if (threadIdx.x == 0) {
;         unsigned* bar = b.bar;
;         __builtin_amdgcn_s_waitcnt(0);
;         unsigned nloc = b.st[0], nx = b.st[1];
;         if (nloc == 0u) { xcd_barrier_complete(bar, b.x, nloc, nx); b.st[0] = nloc; b.st[1] = nx; }
.LBB0_605:
	v_readlane_b32 s1, v250, 60
	s_cmp_eq_u32 s1, 1
	s_cbranch_scc1 .Lswap_toA_l0
	s_waitcnt vmcnt(0)
	s_waitcnt lgkmcnt(0)
	s_barrier
	s_and_saveexec_b64 s[0:1], s[80:81]
	s_cbranch_execz .LBB0_657
	s_add_i32 s2, 0, 0x21fc0
	v_mov_b32_e32 v1, s2
	s_waitcnt vmcnt(0) expcnt(0) lgkmcnt(0)
	ds_read_b32 v3, v1
	s_add_i32 s2, 0, 0x21fc4
	v_mov_b32_e32 v1, s2
	ds_read_b32 v1, v1
	s_waitcnt lgkmcnt(1)
	v_cmp_ne_u32_e32 vcc, 0, v3
	s_cbranch_vccnz .LBB0_621
	v_readlane_b32 s2, v250, 3
	s_mul_i32 s33, s71, s2
	s_add_u32 s2, s86, 0x2310200
	s_addc_u32 s3, s87, 0
	s_add_u32 s4, s86, 0x2310400
	s_addc_u32 s5, s87, 0
	s_add_u32 s6, s86, 0x2310500
	s_addc_u32 s7, s87, 0
	s_add_u32 s8, s86, 0x2310600
	s_addc_u32 s9, s87, 0
	s_add_u32 s10, s86, 0x2310700
	s_addc_u32 s11, s87, 0
	s_add_u32 s12, s86, 0x2310800
	s_addc_u32 s13, s87, 0
	s_add_u32 s14, s86, 0x2310900
	s_addc_u32 s15, s87, 0
	s_add_u32 s16, s86, 0x2310a00
	s_addc_u32 s17, s87, 0
	s_add_u32 s18, s86, 0x2310b00
	s_addc_u32 s19, s87, 0
	s_add_u32 s20, s86, 0x2310c00
	s_addc_u32 s21, s87, 0
	s_add_u32 s22, s86, 0x2310d00
	s_addc_u32 s23, s87, 0
	s_add_u32 s24, s86, 0x2310e00
	s_addc_u32 s25, s87, 0
	s_add_u32 s26, s86, 0x2310f00
	s_addc_u32 s27, s87, 0
	s_add_u32 s28, s86, 0x2311000
	s_addc_u32 s29, s87, 0
	s_add_u32 s30, s86, 0x2311100
	s_addc_u32 s31, s87, 0
	s_add_u32 s34, s86, 0x2311200
	s_addc_u32 s35, s87, 0
	s_add_u32 s36, s86, 0x2311300
	s_mul_i32 s33, s33, s70
	s_addc_u32 s37, s87, 0
	s_mov_b32 s44, 1
	v_mov_b32_e32 v17, 0
	s_branch .LBB0_609
